# k20 + static s_setprio 1 for waves 4-7 from the conv phase through attention (strategy: one static priority raise for the younger half)
# speedup vs baseline: 1.0039x; 1.0039x over previous
; __device__ __forceinline__ void phase_conv(const Params& p, int o, unsigned char* smem, int wave) {
;     const int tid = fresh_tid(wave);
;     c2* buf0 = (c2*)smem;
;     c2* buf1 = (c2*)(smem + 36864);
;     c2* tws = (c2*)(smem + 73728);
;     bf16_t* raw = (bf16_t*)(smem + 106496);
;     const bf16_t* uhy = (const bf16_t*)(p.ws + WS_RB);
;     const bf16_t* z1 = (const bf16_t*)(p.ws + WS_RD);
;     bf16_t* outp = (bf16_t*)(p.ws + (o == 0 ? WS_RD : WS_RE));
;     c2* scr = (c2*)(p.ws + WS_RA + (size_t)blockIdx.x * SCR_PER_BLOCK);
;     const float* normsum = (const float*)(p.ws + WS_NORM);
;     __syncthreads();
;     for (int n = tid; n < 4088; n += NTHR) { int e;
;         if (n < 3584) e = ((n >> 9) + 1) * (n & 511); else if (n < 4032) e = (((n - 3584) >> 6) + 1) * ((n - 3584) & 63) * 8; else e = (((n - 4032) >> 3) + 1) * ((n - 4032) & 7) * 64;
;         float s, c; sincospif((float)e * (1.f / 2048.f), &s, &c); tws[n] = (c2){c, -s}; }
;     __syncthreads();
;     const bool g256 = gridDim.x == 256;
;     const int nrounds = g256 ? 4 : (1024 + gridDim.x - 1) / gridDim.x;
; #pragma unroll 1
;     for (int rd = 0; rd < nrounds; ++rd) {
.LBB0_199:
	s_cmp_lt_u32 s70, 0x100
	s_cbranch_scc1 .Lprio_c
	s_setprio 1
